# v11 with the P5 gated-merge loop at four iterations per trip (16 loads in flight per thread)
# baseline (speedup 1.0000x reference)
; __device__ __forceinline__ unsigned pk2(float lo, float hi) { typedef float f2_ __attribute__((ext_vector_type(2))); const bf16x2n_t b = __builtin_convertvector((f2_){lo, hi}, bf16x2n_t); return __builtin_bit_cast(unsigned, b); }
; __device__ __forceinline__ float bflo(unsigned w) { return __uint_as_float(w << 16); }
; __device__ __forceinline__ float bfhi(unsigned w) { return __uint_as_float(w & 0xffff0000u); }
; template <unsigned MASK> __global__ void __launch_bounds__(NTHREADS, 2) fwd(Args A0) {
;     ...
;             const bf16_t* PG = (const bf16_t*)(ws + WS_PG); bf16_t* Gm = (bf16_t*)(ws + WS_G);
;             const size_t n8 = (size_t)M * D / 8, stride = (size_t)F.G * NTHREADS;
;             for (size_t i = (size_t)F.bid * NTHREADS + F.tid; i < n8; i += stride) {
;                 f32x4 lo4 = (f32x4){0.f, 0.f, 0.f, 0.f}, hi4 = lo4;
; #pragma unroll
;                 for (int z = 0; z < 4; ++z) { const u32x4 w = *(const u32x4*)(PG + (size_t)z * M * D + 8 * i);
;                     lo4[0] += bflo(w.x); lo4[1] += bfhi(w.x); lo4[2] += bflo(w.y); lo4[3] += bfhi(w.y); hi4[0] += bflo(w.z); hi4[1] += bfhi(w.z); hi4[2] += bflo(w.w); hi4[3] += bfhi(w.w); }
;                 u32x4 o; o.x = pk2(lo4[0], lo4[1]); o.y = pk2(lo4[2], lo4[3]); o.z = pk2(hi4[0], hi4[1]); o.w = pk2(hi4[2], hi4[3]);
;                 *(u32x4*)(Gm + 8 * i) = o; }
.LBB0_1810:
	v_lshl_add_u64 v[44:45], v[0:1], 0, s[4:5]
	v_lshl_add_u64 v[44:45], v[44:45], 0, s[4:5]
	v_lshl_add_u64 v[44:45], v[44:45], 0, s[4:5]
	s_mov_b64 s[10:11], 0x280000
	v_cmp_gt_u64_e64 s[100:101], s[10:11], v[44:45]
	s_cmp_eq_u64 s[100:101], 0
	s_cbranch_scc1 .Lp5_single
	v_lshl_add_u64 v[44:45], v[2:3], 0, s[6:7]
	v_lshl_add_u64 v[86:87], v[44:45], 0, s[6:7]
	v_lshl_add_u64 v[88:89], v[86:87], 0, s[6:7]
	v_lshl_add_u64 v[0:1], v[0:1], 0, s[4:5]
	v_lshl_add_u64 v[0:1], v[0:1], 0, s[4:5]
	v_lshl_add_u64 v[0:1], v[0:1], 0, s[4:5]
	v_lshl_add_u64 v[0:1], v[0:1], 0, s[4:5]
	v_add_co_u32_e32 v4, vcc, 0x5000000, v2
	s_nop 0
	s_nop 0
	v_addc_co_u32_e32 v5, vcc, 0, v3, vcc
	v_add_co_u32_e32 v8, vcc, 0x7800000, v2
	global_load_dwordx4 v[4:7], v[4:5], off
	s_nop 0
	v_addc_co_u32_e32 v9, vcc, 0, v3, vcc
	v_add_co_u32_e32 v12, vcc, 0xa000000, v2
	global_load_dwordx4 v[8:11], v[8:9], off
	s_nop 0
	v_addc_co_u32_e32 v13, vcc, 0, v3, vcc
	v_add_co_u32_e32 v16, vcc, 0xc800000, v2
	global_load_dwordx4 v[12:15], v[12:13], off
	s_nop 0
	v_addc_co_u32_e32 v17, vcc, 0, v3, vcc
	global_load_dwordx4 v[16:19], v[16:17], off
	v_add_co_u32_e32 v24, vcc, 0x5000000, v44
	s_nop 0
	s_nop 0
	v_addc_co_u32_e32 v25, vcc, 0, v45, vcc
	v_add_co_u32_e32 v28, vcc, 0x7800000, v44
	global_load_dwordx4 v[24:27], v[24:25], off
	s_nop 0
	v_addc_co_u32_e32 v29, vcc, 0, v45, vcc
	v_add_co_u32_e32 v32, vcc, 0xa000000, v44
	global_load_dwordx4 v[28:31], v[28:29], off
	s_nop 0
	v_addc_co_u32_e32 v33, vcc, 0, v45, vcc
	v_add_co_u32_e32 v36, vcc, 0xc800000, v44
	global_load_dwordx4 v[32:35], v[32:33], off
	s_nop 0
	v_addc_co_u32_e32 v37, vcc, 0, v45, vcc
	global_load_dwordx4 v[36:39], v[36:37], off
	v_add_co_u32_e32 v46, vcc, 0x5000000, v86
	s_nop 0
	s_nop 0
	v_addc_co_u32_e32 v47, vcc, 0, v87, vcc
	v_add_co_u32_e32 v50, vcc, 0x7800000, v86
	global_load_dwordx4 v[46:49], v[46:47], off
	s_nop 0
	v_addc_co_u32_e32 v51, vcc, 0, v87, vcc
	v_add_co_u32_e32 v54, vcc, 0xa000000, v86
	global_load_dwordx4 v[50:53], v[50:51], off
	s_nop 0
	v_addc_co_u32_e32 v55, vcc, 0, v87, vcc
	v_add_co_u32_e32 v58, vcc, 0xc800000, v86
	global_load_dwordx4 v[54:57], v[54:55], off
	s_nop 0
	v_addc_co_u32_e32 v59, vcc, 0, v87, vcc
	global_load_dwordx4 v[58:61], v[58:59], off
	v_add_co_u32_e32 v66, vcc, 0x5000000, v88
	s_nop 0
	s_nop 0
	v_addc_co_u32_e32 v67, vcc, 0, v89, vcc
	v_add_co_u32_e32 v70, vcc, 0x7800000, v88
	global_load_dwordx4 v[66:69], v[66:67], off
	s_nop 0
	v_addc_co_u32_e32 v71, vcc, 0, v89, vcc
	v_add_co_u32_e32 v74, vcc, 0xa000000, v88
	global_load_dwordx4 v[70:73], v[70:71], off
	s_nop 0
	v_addc_co_u32_e32 v75, vcc, 0, v89, vcc
	v_add_co_u32_e32 v78, vcc, 0xc800000, v88
	global_load_dwordx4 v[74:77], v[74:75], off
	s_nop 0
	v_addc_co_u32_e32 v79, vcc, 0, v89, vcc
	global_load_dwordx4 v[78:81], v[78:79], off
	s_mov_b64 s[10:11], 0x27ffff
	v_cmp_lt_u64_e32 vcc, s[10:11], v[0:1]
	s_or_b64 s[8:9], vcc, s[8:9]
	s_waitcnt vmcnt(12)
	v_lshlrev_b32_e32 v20, 16, v4
	v_and_b32_e32 v21, 0xffff0000, v4
	v_lshlrev_b32_e32 v4, 16, v5
	v_and_b32_e32 v5, 0xffff0000, v5
	v_pk_add_f32 v[4:5], v[4:5], 0 op_sel_hi:[1,0]
	v_lshlrev_b32_e32 v22, 16, v8
	v_and_b32_e32 v23, 0xffff0000, v8
	v_lshlrev_b32_e32 v8, 16, v9
	v_and_b32_e32 v9, 0xffff0000, v9
	v_pk_add_f32 v[4:5], v[4:5], v[8:9]
	v_lshlrev_b32_e32 v8, 16, v13
	v_and_b32_e32 v9, 0xffff0000, v13
	v_pk_add_f32 v[4:5], v[4:5], v[8:9]
	v_lshlrev_b32_e32 v8, 16, v17
	v_and_b32_e32 v9, 0xffff0000, v17
	v_pk_add_f32 v[20:21], v[20:21], 0 op_sel_hi:[1,0]
	v_pk_add_f32 v[8:9], v[4:5], v[8:9]
	v_lshlrev_b32_e32 v4, 16, v6
	v_and_b32_e32 v5, 0xffff0000, v6
	v_pk_add_f32 v[20:21], v[20:21], v[22:23]
	v_lshlrev_b32_e32 v22, 16, v12
	v_and_b32_e32 v23, 0xffff0000, v12
	v_pk_add_f32 v[4:5], v[4:5], 0 op_sel_hi:[1,0]
	v_lshlrev_b32_e32 v12, 16, v10
	v_and_b32_e32 v13, 0xffff0000, v10
	v_pk_add_f32 v[4:5], v[4:5], v[12:13]
	v_lshlrev_b32_e32 v12, 16, v14
	v_and_b32_e32 v13, 0xffff0000, v14
	v_pk_add_f32 v[4:5], v[4:5], v[12:13]
	v_lshlrev_b32_e32 v12, 16, v18
	v_and_b32_e32 v13, 0xffff0000, v18
	v_pk_add_f32 v[12:13], v[4:5], v[12:13]
	v_lshlrev_b32_e32 v4, 16, v7
	v_and_b32_e32 v5, 0xffff0000, v7
	v_pk_add_f32 v[4:5], v[4:5], 0 op_sel_hi:[1,0]
	v_lshlrev_b32_e32 v6, 16, v11
	v_and_b32_e32 v7, 0xffff0000, v11
	v_pk_add_f32 v[4:5], v[4:5], v[6:7]
	v_lshlrev_b32_e32 v6, 16, v15
	v_and_b32_e32 v7, 0xffff0000, v15
	v_pk_add_f32 v[20:21], v[20:21], v[22:23]
	v_lshlrev_b32_e32 v22, 16, v16
	v_and_b32_e32 v23, 0xffff0000, v16
	v_pk_add_f32 v[4:5], v[4:5], v[6:7]
	v_lshlrev_b32_e32 v6, 16, v19
	v_and_b32_e32 v7, 0xffff0000, v19
	v_pk_add_f32 v[20:21], v[20:21], v[22:23]
	v_pk_add_f32 v[10:11], v[4:5], v[6:7]
	v_cvt_pk_bf16_f32 v4, v20, v21
	v_cvt_pk_bf16_f32 v5, v8, v9
	v_cvt_pk_bf16_f32 v6, v12, v13
	v_cvt_pk_bf16_f32 v7, v10, v11
	global_store_dwordx4 v[2:3], v[4:7], off
	s_waitcnt vmcnt(9)
; __device__ __forceinline__ unsigned pk2(float lo, float hi) { typedef float f2_ __attribute__((ext_vector_type(2))); const bf16x2n_t b = __builtin_convertvector((f2_){lo, hi}, bf16x2n_t); return __builtin_bit_cast(unsigned, b); }
; __device__ __forceinline__ float bflo(unsigned w) { return __uint_as_float(w << 16); }
; __device__ __forceinline__ float bfhi(unsigned w) { return __uint_as_float(w & 0xffff0000u); }
; template <unsigned MASK> __global__ void __launch_bounds__(NTHREADS, 2) fwd(Args A0) {
;     ...
;             const bf16_t* PG = (const bf16_t*)(ws + WS_PG); bf16_t* Gm = (bf16_t*)(ws + WS_G);
;             const size_t n8 = (size_t)M * D / 8, stride = (size_t)F.G * NTHREADS;
;             for (size_t i = (size_t)F.bid * NTHREADS + F.tid; i < n8; i += stride) {
;                 f32x4 lo4 = (f32x4){0.f, 0.f, 0.f, 0.f}, hi4 = lo4;
; #pragma unroll
;                 for (int z = 0; z < 4; ++z) { const u32x4 w = *(const u32x4*)(PG + (size_t)z * M * D + 8 * i);
;                     lo4[0] += bflo(w.x); lo4[1] += bfhi(w.x); lo4[2] += bflo(w.y); lo4[3] += bfhi(w.y); hi4[0] += bflo(w.z); hi4[1] += bfhi(w.z); hi4[2] += bflo(w.w); hi4[3] += bfhi(w.w); }
;                 u32x4 o; o.x = pk2(lo4[0], lo4[1]); o.y = pk2(lo4[2], lo4[3]); o.z = pk2(hi4[0], hi4[1]); o.w = pk2(hi4[2], hi4[3]);
;                 *(u32x4*)(Gm + 8 * i) = o; }
	v_lshlrev_b32_e32 v40, 16, v24
	v_and_b32_e32 v41, 0xffff0000, v24
	v_lshlrev_b32_e32 v24, 16, v25
	v_and_b32_e32 v25, 0xffff0000, v25
	v_pk_add_f32 v[24:25], v[24:25], 0 op_sel_hi:[1,0]
	v_lshlrev_b32_e32 v42, 16, v28
	v_and_b32_e32 v43, 0xffff0000, v28
	v_lshlrev_b32_e32 v28, 16, v29
	v_and_b32_e32 v29, 0xffff0000, v29
	v_pk_add_f32 v[24:25], v[24:25], v[28:29]
	v_lshlrev_b32_e32 v28, 16, v33
	v_and_b32_e32 v29, 0xffff0000, v33
	v_pk_add_f32 v[24:25], v[24:25], v[28:29]
	v_lshlrev_b32_e32 v28, 16, v37
	v_and_b32_e32 v29, 0xffff0000, v37
	v_pk_add_f32 v[40:41], v[40:41], 0 op_sel_hi:[1,0]
	v_pk_add_f32 v[28:29], v[24:25], v[28:29]
	v_lshlrev_b32_e32 v24, 16, v26
	v_and_b32_e32 v25, 0xffff0000, v26
	v_pk_add_f32 v[40:41], v[40:41], v[42:43]
	v_lshlrev_b32_e32 v42, 16, v32
	v_and_b32_e32 v43, 0xffff0000, v32
	v_pk_add_f32 v[24:25], v[24:25], 0 op_sel_hi:[1,0]
	v_lshlrev_b32_e32 v32, 16, v30
	v_and_b32_e32 v33, 0xffff0000, v30
	v_pk_add_f32 v[24:25], v[24:25], v[32:33]
	v_lshlrev_b32_e32 v32, 16, v34
	v_and_b32_e32 v33, 0xffff0000, v34
	v_pk_add_f32 v[24:25], v[24:25], v[32:33]
	v_lshlrev_b32_e32 v32, 16, v38
	v_and_b32_e32 v33, 0xffff0000, v38
	v_pk_add_f32 v[32:33], v[24:25], v[32:33]
	v_lshlrev_b32_e32 v24, 16, v27
	v_and_b32_e32 v25, 0xffff0000, v27
	v_pk_add_f32 v[24:25], v[24:25], 0 op_sel_hi:[1,0]
	v_lshlrev_b32_e32 v26, 16, v31
	v_and_b32_e32 v27, 0xffff0000, v31
	v_pk_add_f32 v[24:25], v[24:25], v[26:27]
	v_lshlrev_b32_e32 v26, 16, v35
	v_and_b32_e32 v27, 0xffff0000, v35
	v_pk_add_f32 v[40:41], v[40:41], v[42:43]
	v_lshlrev_b32_e32 v42, 16, v36
	v_and_b32_e32 v43, 0xffff0000, v36
	v_pk_add_f32 v[24:25], v[24:25], v[26:27]
	v_lshlrev_b32_e32 v26, 16, v39
	v_and_b32_e32 v27, 0xffff0000, v39
	v_pk_add_f32 v[40:41], v[40:41], v[42:43]
	v_pk_add_f32 v[30:31], v[24:25], v[26:27]
	v_cvt_pk_bf16_f32 v24, v40, v41
	v_cvt_pk_bf16_f32 v25, v28, v29
	v_cvt_pk_bf16_f32 v26, v32, v33
	v_cvt_pk_bf16_f32 v27, v30, v31
	global_store_dwordx4 v[44:45], v[24:27], off
	s_waitcnt vmcnt(6)
	v_lshlrev_b32_e32 v62, 16, v46
	v_and_b32_e32 v63, 0xffff0000, v46
	v_lshlrev_b32_e32 v46, 16, v47
	v_and_b32_e32 v47, 0xffff0000, v47
	v_pk_add_f32 v[46:47], v[46:47], 0 op_sel_hi:[1,0]
	v_lshlrev_b32_e32 v64, 16, v50
	v_and_b32_e32 v65, 0xffff0000, v50
	v_lshlrev_b32_e32 v50, 16, v51
	v_and_b32_e32 v51, 0xffff0000, v51
	v_pk_add_f32 v[46:47], v[46:47], v[50:51]
	v_lshlrev_b32_e32 v50, 16, v55
	v_and_b32_e32 v51, 0xffff0000, v55
	v_pk_add_f32 v[46:47], v[46:47], v[50:51]
	v_lshlrev_b32_e32 v50, 16, v59
	v_and_b32_e32 v51, 0xffff0000, v59
	v_pk_add_f32 v[62:63], v[62:63], 0 op_sel_hi:[1,0]
	v_pk_add_f32 v[50:51], v[46:47], v[50:51]
	v_lshlrev_b32_e32 v46, 16, v48
	v_and_b32_e32 v47, 0xffff0000, v48
	v_pk_add_f32 v[62:63], v[62:63], v[64:65]
	v_lshlrev_b32_e32 v64, 16, v54
	v_and_b32_e32 v65, 0xffff0000, v54
	v_pk_add_f32 v[46:47], v[46:47], 0 op_sel_hi:[1,0]
	v_lshlrev_b32_e32 v54, 16, v52
	v_and_b32_e32 v55, 0xffff0000, v52
	v_pk_add_f32 v[46:47], v[46:47], v[54:55]
	v_lshlrev_b32_e32 v54, 16, v56
	v_and_b32_e32 v55, 0xffff0000, v56
	v_pk_add_f32 v[46:47], v[46:47], v[54:55]
	v_lshlrev_b32_e32 v54, 16, v60
	v_and_b32_e32 v55, 0xffff0000, v60
	v_pk_add_f32 v[54:55], v[46:47], v[54:55]
	v_lshlrev_b32_e32 v46, 16, v49
	v_and_b32_e32 v47, 0xffff0000, v49
	v_pk_add_f32 v[46:47], v[46:47], 0 op_sel_hi:[1,0]
	v_lshlrev_b32_e32 v48, 16, v53
	v_and_b32_e32 v49, 0xffff0000, v53
	v_pk_add_f32 v[46:47], v[46:47], v[48:49]
	v_lshlrev_b32_e32 v48, 16, v57
	v_and_b32_e32 v49, 0xffff0000, v57
	v_pk_add_f32 v[62:63], v[62:63], v[64:65]
	v_lshlrev_b32_e32 v64, 16, v58
	v_and_b32_e32 v65, 0xffff0000, v58
	v_pk_add_f32 v[46:47], v[46:47], v[48:49]
	v_lshlrev_b32_e32 v48, 16, v61
	v_and_b32_e32 v49, 0xffff0000, v61
	v_pk_add_f32 v[62:63], v[62:63], v[64:65]
	v_pk_add_f32 v[52:53], v[46:47], v[48:49]
	v_cvt_pk_bf16_f32 v46, v62, v63
	v_cvt_pk_bf16_f32 v47, v50, v51
	v_cvt_pk_bf16_f32 v48, v54, v55
	v_cvt_pk_bf16_f32 v49, v52, v53
	global_store_dwordx4 v[86:87], v[46:49], off
	s_waitcnt vmcnt(3)
	v_lshlrev_b32_e32 v82, 16, v66
	v_and_b32_e32 v83, 0xffff0000, v66
	v_lshlrev_b32_e32 v66, 16, v67
	v_and_b32_e32 v67, 0xffff0000, v67
	v_pk_add_f32 v[66:67], v[66:67], 0 op_sel_hi:[1,0]
	v_lshlrev_b32_e32 v84, 16, v70
	v_and_b32_e32 v85, 0xffff0000, v70
	v_lshlrev_b32_e32 v70, 16, v71
	v_and_b32_e32 v71, 0xffff0000, v71
	v_pk_add_f32 v[66:67], v[66:67], v[70:71]
	v_lshlrev_b32_e32 v70, 16, v75
	v_and_b32_e32 v71, 0xffff0000, v75
	v_pk_add_f32 v[66:67], v[66:67], v[70:71]
	v_lshlrev_b32_e32 v70, 16, v79
	v_and_b32_e32 v71, 0xffff0000, v79
	v_pk_add_f32 v[82:83], v[82:83], 0 op_sel_hi:[1,0]
	v_pk_add_f32 v[70:71], v[66:67], v[70:71]
	v_lshlrev_b32_e32 v66, 16, v68
	v_and_b32_e32 v67, 0xffff0000, v68
	v_pk_add_f32 v[82:83], v[82:83], v[84:85]
	v_lshlrev_b32_e32 v84, 16, v74
	v_and_b32_e32 v85, 0xffff0000, v74
	v_pk_add_f32 v[66:67], v[66:67], 0 op_sel_hi:[1,0]
	v_lshlrev_b32_e32 v74, 16, v72
	v_and_b32_e32 v75, 0xffff0000, v72
	v_pk_add_f32 v[66:67], v[66:67], v[74:75]
	v_lshlrev_b32_e32 v74, 16, v76
	v_and_b32_e32 v75, 0xffff0000, v76
	v_pk_add_f32 v[66:67], v[66:67], v[74:75]
	v_lshlrev_b32_e32 v74, 16, v80
	v_and_b32_e32 v75, 0xffff0000, v80
	v_pk_add_f32 v[74:75], v[66:67], v[74:75]
	v_lshlrev_b32_e32 v66, 16, v69
	v_and_b32_e32 v67, 0xffff0000, v69
	v_pk_add_f32 v[66:67], v[66:67], 0 op_sel_hi:[1,0]
	v_lshlrev_b32_e32 v68, 16, v73
	v_and_b32_e32 v69, 0xffff0000, v73
	v_pk_add_f32 v[66:67], v[66:67], v[68:69]
	v_lshlrev_b32_e32 v68, 16, v77
	v_and_b32_e32 v69, 0xffff0000, v77
	v_pk_add_f32 v[82:83], v[82:83], v[84:85]
	v_lshlrev_b32_e32 v84, 16, v78
	v_and_b32_e32 v85, 0xffff0000, v78
	v_pk_add_f32 v[66:67], v[66:67], v[68:69]
	v_lshlrev_b32_e32 v68, 16, v81
	v_and_b32_e32 v69, 0xffff0000, v81
	v_pk_add_f32 v[82:83], v[82:83], v[84:85]
	v_pk_add_f32 v[72:73], v[66:67], v[68:69]
	v_cvt_pk_bf16_f32 v66, v82, v83
	v_cvt_pk_bf16_f32 v67, v70, v71
	v_cvt_pk_bf16_f32 v68, v74, v75
	v_cvt_pk_bf16_f32 v69, v72, v73
	global_store_dwordx4 v[88:89], v[66:69], off
	v_lshl_add_u64 v[2:3], v[88:89], 0, s[6:7]
	s_andn2_b64 exec, exec, s[8:9]
	s_cbranch_execnz .LBB0_1810
	s_branch .Lp5_done
